# as v48 plus: the pending next-ticket atomic is left in flight across the attention store tail (counted wait)
# baseline (speedup 1.0000x reference)
; DI unsigned pk2(float a, float b) { f32x2 v = {a, b}; bf2_t r = __builtin_convertvector(v, bf2_t); return __builtin_bit_cast(unsigned, r); }
; DI void attn_unit(const Params& p, int l, int b, int qtp, int grp, char* smem) {
;     ...
;   const int gcol = (grp == 2 ? 0 : grp == 1 ? 256 : grp == 0 ? 512 : 768) + w * 64 + 4 * h;
;   bf16_t* mrow = (bf16_t*)(p.ws + OFF_MIX) + (tok0 + qpos) * DM + gcol;
; #pragma unroll
;   for (int g = 0; g < 4; ++g) {
;     u32x2 a = {pk2(o0[4 * g], o0[4 * g + 1]), pk2(o0[4 * g + 2], o0[4 * g + 3])};
;     u32x2 c = {pk2(o1[4 * g], o1[4 * g + 1]), pk2(o1[4 * g + 2], o1[4 * g + 3])};
;     *(u32x2*)(mrow + 8 * g) = a;
;     *(u32x2*)(mrow + 32 + 8 * g) = c;
;   }
;   __syncthreads();
.Lpf3_skip:
	s_mov_b64 exec, -1
	v_readlane_b32 s1, v244, 21
	s_cmp_lg_u32 s1, 1
	s_cselect_b32 s2, s0, 0x100
	v_readlane_b32 s0, v244, 9
	v_readlane_b32 s1, v244, 10
	s_and_b64 s[0:1], s[0:1], exec
	s_cselect_b32 s0, 0, s2
	v_or3_b32 v0, v159, v220, s0
	v_readlane_b32 s0, v246, 16
	v_lshlrev_b64 v[34:35], 11, v[156:157]
	v_readlane_b32 s1, v246, 17
	s_cmp_eq_u32 s99, 1
	s_cbranch_scc1 .Lst_w1
	s_waitcnt vmcnt(0)
	s_branch .Lst_w2
.Lst_w1:
	s_waitcnt vmcnt(1)
.Lst_w2:
	v_lshl_add_u64 v[34:35], s[0:1], 0, v[34:35]
	v_lshl_add_u64 v[34:35], v[0:1], 1, v[34:35]
	v_cvt_pk_bf16_f32 v36, v18, v19
	v_cvt_pk_bf16_f32 v37, v20, v21
	v_cvt_pk_bf16_f32 v38, v22, v23
	v_cvt_pk_bf16_f32 v39, v24, v25
	v_cvt_pk_bf16_f32 v40, v26, v27
	v_cvt_pk_bf16_f32 v41, v28, v29
	v_cvt_pk_bf16_f32 v42, v30, v31
	v_cvt_pk_bf16_f32 v43, v32, v33
	v_cvt_pk_bf16_f32 v44, v2, v3
	v_cvt_pk_bf16_f32 v45, v4, v5
	v_cvt_pk_bf16_f32 v46, v6, v7
	v_cvt_pk_bf16_f32 v47, v8, v9
	v_cvt_pk_bf16_f32 v48, v10, v11
	v_cvt_pk_bf16_f32 v49, v12, v13
	v_cvt_pk_bf16_f32 v50, v14, v15
	v_cvt_pk_bf16_f32 v51, v16, v17
	v_and_b32_e32 v52, 32, v203
	v_lshrrev_b32_e32 v52, 2, v52
	v_mov_b32_e32 v53, 0
	v_lshl_add_u64 v[34:35], v[34:35], 0, v[52:53]
	v_permlane32_swap_b32_e32 v36, v38
	v_permlane32_swap_b32_e32 v37, v39
	v_permlane32_swap_b32_e32 v40, v42
	v_permlane32_swap_b32_e32 v41, v43
	v_permlane32_swap_b32_e32 v44, v46
	v_permlane32_swap_b32_e32 v45, v47
	v_permlane32_swap_b32_e32 v48, v50
	v_permlane32_swap_b32_e32 v49, v51
	global_store_dwordx4 v[34:35], v[36:39], off
	global_store_dwordx4 v[34:35], v[40:43], off offset:32
	global_store_dwordx4 v[34:35], v[44:47], off offset:64
	global_store_dwordx4 v[34:35], v[48:51], off offset:96
	s_barrier
